# v035 + attention unit boundary: store-drain s_waitcnt vmcnt(0) before the end-of-unit barrier removed (drain overlaps the next unit's Q/K/V prologue loads)
# baseline (speedup 1.0000x reference)
.LBB0_701:
	s_or_b64 exec, exec, s[12:13]
	v_mov_b32_e32 v3, v150
	s_waitcnt lgkmcnt(0)
	ds_read_b128 v[68:71], v154
	ds_read_b128 v[72:75], v154 offset:32
	s_lshl_b64 s[2:3], s[2:3], 1
	s_add_u32 s2, s38, s2
	s_addc_u32 s3, s39, s3
	s_waitcnt lgkmcnt(0)
	v_rcp_f32_e32 v68, v68
	s_lshl_b32 s12, s16, 1
	s_add_u32 s2, s2, s12
	s_addc_u32 s3, s3, 0
	v_mul_f32_e32 v52, v52, v68
	v_bfe_u32 v76, v52, 16, 1
	v_lshlrev_b32_e32 v3, 1, v3
	v_add3_u32 v52, v52, v76, s47
	v_mul_f32_e32 v36, v36, v68
	global_store_short_d16_hi v3, v52, s[2:3]
	v_bfe_u32 v52, v36, 16, 1
	v_add3_u32 v36, v36, v52, s47
	v_add_u32_e32 v52, 64, v3
	v_mul_f32_e32 v20, v20, v68
	global_store_short_d16_hi v52, v36, s[2:3]
	v_bfe_u32 v36, v20, 16, 1
	v_add3_u32 v20, v20, v36, s47
	v_add_u32_e32 v36, 0x80, v3
	v_mul_f32_e32 v4, v4, v68
	global_store_short_d16_hi v36, v20, s[2:3]
	v_bfe_u32 v20, v4, 16, 1
	v_add3_u32 v4, v4, v20, s47
	v_rcp_f32_e32 v20, v69
	v_add_u32_e32 v36, 0xc0, v3
	global_store_short_d16_hi v36, v4, s[2:3]
	v_add_u32_e32 v4, 0x1000, v3
	v_mul_f32_e32 v36, v53, v20
	v_bfe_u32 v52, v36, 16, 1
	v_add3_u32 v36, v36, v52, s47
	global_store_short_d16_hi v4, v36, s[2:3]
	v_mul_f32_e32 v4, v37, v20
	v_bfe_u32 v36, v4, 16, 1
	v_add3_u32 v4, v4, v36, s47
	v_add_u32_e32 v36, 0x1040, v3
	global_store_short_d16_hi v36, v4, s[2:3]
	v_mul_f32_e32 v4, v21, v20
	v_bfe_u32 v21, v4, 16, 1
	v_add3_u32 v4, v4, v21, s47
	v_add_u32_e32 v21, 0x1080, v3
	global_store_short_d16_hi v21, v4, s[2:3]
	v_mul_f32_e32 v4, v5, v20
	v_bfe_u32 v5, v4, 16, 1
	v_add3_u32 v4, v4, v5, s47
	v_rcp_f32_e32 v5, v70
	v_add_u32_e32 v20, 0x10c0, v3
	global_store_short_d16_hi v20, v4, s[2:3]
	v_add_u32_e32 v4, 0x2000, v3
	v_mul_f32_e32 v20, v54, v5
	v_bfe_u32 v21, v20, 16, 1
	v_add3_u32 v20, v20, v21, s47
	global_store_short_d16_hi v4, v20, s[2:3]
	v_mul_f32_e32 v4, v38, v5
	v_bfe_u32 v20, v4, 16, 1
	v_add3_u32 v4, v4, v20, s47
	v_add_u32_e32 v20, 0x2040, v3
	global_store_short_d16_hi v20, v4, s[2:3]
	v_mul_f32_e32 v4, v22, v5
	v_bfe_u32 v20, v4, 16, 1
	v_add3_u32 v4, v4, v20, s47
	v_add_u32_e32 v20, 0x2080, v3
	global_store_short_d16_hi v20, v4, s[2:3]
	v_mul_f32_e32 v4, v6, v5
	v_bfe_u32 v5, v4, 16, 1
	v_add3_u32 v4, v4, v5, s47
	v_rcp_f32_e32 v5, v71
	v_add_u32_e32 v6, 0x20c0, v3
	global_store_short_d16_hi v6, v4, s[2:3]
	v_add_u32_e32 v4, 0x3000, v3
	v_mul_f32_e32 v6, v55, v5
	v_bfe_u32 v20, v6, 16, 1
	v_add3_u32 v6, v6, v20, s47
	global_store_short_d16_hi v4, v6, s[2:3]
	v_mul_f32_e32 v4, v39, v5
	v_bfe_u32 v6, v4, 16, 1
	v_add3_u32 v4, v4, v6, s47
	v_add_u32_e32 v6, 0x3040, v3
	global_store_short_d16_hi v6, v4, s[2:3]
	v_mul_f32_e32 v4, v23, v5
	v_bfe_u32 v6, v4, 16, 1
	v_add3_u32 v4, v4, v6, s47
	v_add_u32_e32 v6, 0x3080, v3
	global_store_short_d16_hi v6, v4, s[2:3]
	v_mul_f32_e32 v4, v7, v5
	v_bfe_u32 v5, v4, 16, 1
	v_add3_u32 v4, v4, v5, s47
	v_rcp_f32_e32 v5, v72
	v_add_u32_e32 v6, 0x30c0, v3
	global_store_short_d16_hi v6, v4, s[2:3]
	v_add_u32_e32 v4, 0x8000, v3
	v_mul_f32_e32 v6, v56, v5
	v_bfe_u32 v7, v6, 16, 1
	v_add3_u32 v6, v6, v7, s47
	global_store_short_d16_hi v4, v6, s[2:3]
	v_mul_f32_e32 v4, v40, v5
	v_bfe_u32 v6, v4, 16, 1
	v_add3_u32 v4, v4, v6, s47
	v_add_u32_e32 v6, 0x8040, v3
	global_store_short_d16_hi v6, v4, s[2:3]
	v_mul_f32_e32 v4, v24, v5
	v_bfe_u32 v6, v4, 16, 1
	v_add3_u32 v4, v4, v6, s47
	v_add_u32_e32 v6, 0x8080, v3
	global_store_short_d16_hi v6, v4, s[2:3]
	v_mul_f32_e32 v4, v8, v5
	v_bfe_u32 v5, v4, 16, 1
	v_add3_u32 v4, v4, v5, s47
	v_rcp_f32_e32 v5, v73
	v_add_u32_e32 v6, 0x80c0, v3
	global_store_short_d16_hi v6, v4, s[2:3]
	v_add_u32_e32 v4, 0x9000, v3
	v_mul_f32_e32 v6, v57, v5
	v_bfe_u32 v7, v6, 16, 1
	v_add3_u32 v6, v6, v7, s47
	global_store_short_d16_hi v4, v6, s[2:3]
	v_mul_f32_e32 v4, v41, v5
	v_bfe_u32 v6, v4, 16, 1
	v_add3_u32 v4, v4, v6, s47
	v_add_u32_e32 v6, 0x9040, v3
	global_store_short_d16_hi v6, v4, s[2:3]
	v_mul_f32_e32 v4, v25, v5
	v_bfe_u32 v6, v4, 16, 1
	v_add3_u32 v4, v4, v6, s47
	v_add_u32_e32 v6, 0x9080, v3
	global_store_short_d16_hi v6, v4, s[2:3]
	v_mul_f32_e32 v4, v9, v5
	v_bfe_u32 v5, v4, 16, 1
	v_add3_u32 v4, v4, v5, s47
	v_rcp_f32_e32 v5, v74
	v_add_u32_e32 v6, 0x90c0, v3
	global_store_short_d16_hi v6, v4, s[2:3]
	v_add_u32_e32 v4, 0xa000, v3
	v_mul_f32_e32 v6, v58, v5
	v_bfe_u32 v7, v6, 16, 1
	v_add3_u32 v6, v6, v7, s47
	global_store_short_d16_hi v4, v6, s[2:3]
	v_mul_f32_e32 v4, v42, v5
	v_bfe_u32 v6, v4, 16, 1
	v_add3_u32 v4, v4, v6, s47
	v_add_u32_e32 v6, 0xa040, v3
	global_store_short_d16_hi v6, v4, s[2:3]
	v_mul_f32_e32 v4, v26, v5
	v_bfe_u32 v6, v4, 16, 1
	v_add3_u32 v4, v4, v6, s47
	v_add_u32_e32 v6, 0xa080, v3
	v_rcp_f32_e32 v8, v75
	global_store_short_d16_hi v6, v4, s[2:3]
	v_mul_f32_e32 v4, v10, v5
	v_bfe_u32 v5, v4, 16, 1
	v_add3_u32 v4, v4, v5, s47
	v_add_u32_e32 v5, 0xa0c0, v3
	global_store_short_d16_hi v5, v4, s[2:3]
	v_mul_f32_e32 v5, v59, v8
	v_bfe_u32 v6, v5, 16, 1
	v_add_u32_e32 v4, 0xb000, v3
	v_add3_u32 v5, v5, v6, s47
	global_store_short_d16_hi v4, v5, s[2:3]
	v_mul_f32_e32 v4, v43, v8
	v_bfe_u32 v5, v4, 16, 1
	v_add3_u32 v4, v4, v5, s47
	v_add_u32_e32 v5, 0xb040, v3
	global_store_short_d16_hi v5, v4, s[2:3]
	v_mul_f32_e32 v4, v27, v8
	v_bfe_u32 v5, v4, 16, 1
	v_add3_u32 v4, v4, v5, s47
	v_add_u32_e32 v5, 0xb080, v3
	global_store_short_d16_hi v5, v4, s[2:3]
	ds_read_b128 v[4:7], v154 offset:64
	v_mul_f32_e32 v8, v11, v8
	v_bfe_u32 v9, v8, 16, 1
	v_add3_u32 v20, v8, v9, s47
	ds_read_b128 v[8:11], v154 offset:96
	s_waitcnt lgkmcnt(0)
	v_rcp_f32_e32 v4, v4
	v_add_u32_e32 v21, 0xb0c0, v3
	global_store_short_d16_hi v21, v20, s[2:3]
	v_add_u32_e32 v20, 0x10000, v3
	v_mul_f32_e32 v21, v60, v4
	v_bfe_u32 v22, v21, 16, 1
	v_add3_u32 v21, v21, v22, s47
	global_store_short_d16_hi v20, v21, s[2:3]
	v_mul_f32_e32 v20, v44, v4
	v_bfe_u32 v21, v20, 16, 1
	v_add3_u32 v20, v20, v21, s47
	v_add_u32_e32 v21, 0x10040, v3
	v_rcp_f32_e32 v5, v5
	global_store_short_d16_hi v21, v20, s[2:3]
	v_mul_f32_e32 v20, v28, v4
	v_mul_f32_e32 v4, v12, v4
	v_bfe_u32 v12, v4, 16, 1
	v_bfe_u32 v21, v20, 16, 1
	v_add3_u32 v4, v4, v12, s47
	v_add_u32_e32 v12, 0x100c0, v3
	v_add3_u32 v20, v20, v21, s47
	v_add_u32_e32 v21, 0x10080, v3
	global_store_short_d16_hi v12, v4, s[2:3]
	v_mul_f32_e32 v12, v61, v5
	global_store_short_d16_hi v21, v20, s[2:3]
	v_bfe_u32 v20, v12, 16, 1
	v_add_u32_e32 v4, 0x11000, v3
	v_add3_u32 v12, v12, v20, s47
	global_store_short_d16_hi v4, v12, s[2:3]
	v_mul_f32_e32 v4, v45, v5
	v_bfe_u32 v12, v4, 16, 1
	v_add3_u32 v4, v4, v12, s47
	v_add_u32_e32 v12, 0x11040, v3
	global_store_short_d16_hi v12, v4, s[2:3]
	v_mul_f32_e32 v4, v29, v5
	v_bfe_u32 v12, v4, 16, 1
	v_add3_u32 v4, v4, v12, s47
	v_add_u32_e32 v12, 0x11080, v3
	global_store_short_d16_hi v12, v4, s[2:3]
	v_mul_f32_e32 v4, v13, v5
	v_bfe_u32 v5, v4, 16, 1
	v_add3_u32 v4, v4, v5, s47
	v_rcp_f32_e32 v5, v6
	v_add_u32_e32 v6, 0x110c0, v3
	global_store_short_d16_hi v6, v4, s[2:3]
	v_add_u32_e32 v4, 0x12000, v3
	v_mul_f32_e32 v6, v62, v5
	v_bfe_u32 v12, v6, 16, 1
	v_add3_u32 v6, v6, v12, s47
	global_store_short_d16_hi v4, v6, s[2:3]
	v_mul_f32_e32 v4, v46, v5
	v_bfe_u32 v6, v4, 16, 1
	v_add3_u32 v4, v4, v6, s47
	v_add_u32_e32 v6, 0x12040, v3
	global_store_short_d16_hi v6, v4, s[2:3]
	v_mul_f32_e32 v4, v30, v5
	v_bfe_u32 v6, v4, 16, 1
	v_add3_u32 v4, v4, v6, s47
	v_add_u32_e32 v6, 0x12080, v3
	global_store_short_d16_hi v6, v4, s[2:3]
	v_mul_f32_e32 v4, v14, v5
	v_bfe_u32 v5, v4, 16, 1
	v_add3_u32 v4, v4, v5, s47
	v_rcp_f32_e32 v5, v7
	v_add_u32_e32 v6, 0x120c0, v3
	global_store_short_d16_hi v6, v4, s[2:3]
	v_add_u32_e32 v4, 0x13000, v3
	v_mul_f32_e32 v6, v63, v5
	v_bfe_u32 v7, v6, 16, 1
	v_add3_u32 v6, v6, v7, s47
	global_store_short_d16_hi v4, v6, s[2:3]
	v_mul_f32_e32 v4, v47, v5
	v_bfe_u32 v6, v4, 16, 1
	v_add3_u32 v4, v4, v6, s47
	v_add_u32_e32 v6, 0x13040, v3
	global_store_short_d16_hi v6, v4, s[2:3]
	v_mul_f32_e32 v4, v31, v5
	v_bfe_u32 v6, v4, 16, 1
	v_add3_u32 v4, v4, v6, s47
	v_add_u32_e32 v6, 0x13080, v3
	global_store_short_d16_hi v6, v4, s[2:3]
	v_mul_f32_e32 v4, v15, v5
	v_bfe_u32 v5, v4, 16, 1
	v_add3_u32 v4, v4, v5, s47
	v_rcp_f32_e32 v5, v8
	v_add_u32_e32 v6, 0x130c0, v3
	global_store_short_d16_hi v6, v4, s[2:3]
	v_add_u32_e32 v4, 0x18000, v3
	v_mul_f32_e32 v6, v64, v5
	v_bfe_u32 v7, v6, 16, 1
	v_add3_u32 v6, v6, v7, s47
	global_store_short_d16_hi v4, v6, s[2:3]
	v_mul_f32_e32 v4, v48, v5
	v_bfe_u32 v6, v4, 16, 1
	v_add3_u32 v4, v4, v6, s47
	v_add_u32_e32 v6, 0x18040, v3
	global_store_short_d16_hi v6, v4, s[2:3]
	v_mul_f32_e32 v4, v32, v5
	v_bfe_u32 v6, v4, 16, 1
	v_add3_u32 v4, v4, v6, s47
	v_add_u32_e32 v6, 0x18080, v3
	global_store_short_d16_hi v6, v4, s[2:3]
	v_mul_f32_e32 v4, v16, v5
	v_bfe_u32 v5, v4, 16, 1
	v_add3_u32 v4, v4, v5, s47
	v_rcp_f32_e32 v5, v9
	v_add_u32_e32 v6, 0x180c0, v3
	global_store_short_d16_hi v6, v4, s[2:3]
	v_add_u32_e32 v4, 0x19000, v3
	v_mul_f32_e32 v6, v65, v5
	v_bfe_u32 v7, v6, 16, 1
	v_add3_u32 v6, v6, v7, s47
	global_store_short_d16_hi v4, v6, s[2:3]
	v_mul_f32_e32 v4, v49, v5
	v_bfe_u32 v6, v4, 16, 1
	v_add3_u32 v4, v4, v6, s47
	v_add_u32_e32 v6, 0x19040, v3
	global_store_short_d16_hi v6, v4, s[2:3]
	v_mul_f32_e32 v4, v33, v5
	v_bfe_u32 v6, v4, 16, 1
	v_add3_u32 v4, v4, v6, s47
	v_add_u32_e32 v6, 0x19080, v3
	global_store_short_d16_hi v6, v4, s[2:3]
	v_mul_f32_e32 v4, v17, v5
	v_bfe_u32 v5, v4, 16, 1
	v_add3_u32 v4, v4, v5, s47
	v_rcp_f32_e32 v5, v10
	v_add_u32_e32 v6, 0x190c0, v3
	global_store_short_d16_hi v6, v4, s[2:3]
	v_add_u32_e32 v4, 0x1a000, v3
	v_mul_f32_e32 v6, v66, v5
	v_bfe_u32 v7, v6, 16, 1
	v_add3_u32 v6, v6, v7, s47
	global_store_short_d16_hi v4, v6, s[2:3]
	v_mul_f32_e32 v4, v50, v5
	v_bfe_u32 v6, v4, 16, 1
	v_add3_u32 v4, v4, v6, s47
	v_add_u32_e32 v6, 0x1a040, v3
	global_store_short_d16_hi v6, v4, s[2:3]
	v_mul_f32_e32 v4, v34, v5
	v_bfe_u32 v6, v4, 16, 1
	v_add3_u32 v4, v4, v6, s47
	v_add_u32_e32 v6, 0x1a080, v3
	global_store_short_d16_hi v6, v4, s[2:3]
	v_mul_f32_e32 v4, v18, v5
	v_bfe_u32 v5, v4, 16, 1
	v_add3_u32 v4, v4, v5, s47
	v_rcp_f32_e32 v5, v11
	v_add_u32_e32 v6, 0x1a0c0, v3
	global_store_short_d16_hi v6, v4, s[2:3]
	v_add_u32_e32 v4, 0x1b000, v3
	v_mul_f32_e32 v6, v67, v5
	v_bfe_u32 v7, v6, 16, 1
	v_add3_u32 v6, v6, v7, s47
	global_store_short_d16_hi v4, v6, s[2:3]
	v_mul_f32_e32 v4, v51, v5
	v_bfe_u32 v6, v4, 16, 1
	v_add3_u32 v4, v4, v6, s47
	v_add_u32_e32 v6, 0x1b040, v3
	global_store_short_d16_hi v6, v4, s[2:3]
	v_mul_f32_e32 v4, v35, v5
	v_bfe_u32 v6, v4, 16, 1
	v_add3_u32 v4, v4, v6, s47
	v_add_u32_e32 v6, 0x1b080, v3
	global_store_short_d16_hi v6, v4, s[2:3]
	v_mul_f32_e32 v4, v19, v5
	v_bfe_u32 v5, v4, 16, 1
	v_add3_u32 v4, v4, v5, s47
	v_add_u32_e32 v3, 0x1b0c0, v3
	global_store_short_d16_hi v3, v4, s[2:3]
	s_waitcnt lgkmcnt(0)
	s_add_i32 s50, s50, s96
	s_add_i32 s28, s28, s29
	s_cmpk_gt_i32 s50, 0x1ff
	s_nop 0
	s_barrier
	s_cbranch_scc1 .LBB0_723

.LBB0_1574:
	s_or_b64 exec, exec, s[2:3]
	v_mov_b32_e32 v74, v166
	s_waitcnt lgkmcnt(0)
	ds_read_b128 v[66:69], v173
	ds_read_b128 v[70:73], v173 offset:32
	s_lshl_b64 s[2:3], s[16:17], 12
	s_add_u32 s2, s38, s2
	s_addc_u32 s3, s39, s3
	s_waitcnt lgkmcnt(0)
	v_rcp_f32_e32 v66, v66
	s_lshl_b32 s6, s50, 1
	s_add_u32 s2, s2, s6
	s_addc_u32 s3, s3, 0
	v_mul_f32_e32 v2, v2, v66
	v_bfe_u32 v75, v2, 16, 1
	v_lshlrev_b32_e32 v74, 1, v74
	v_add3_u32 v2, v2, v75, s46
	global_store_short_d16_hi v74, v2, s[2:3]
	v_mul_f32_e32 v2, v50, v66
	v_bfe_u32 v50, v2, 16, 1
	v_add3_u32 v2, v2, v50, s46
	v_add_u32_e32 v50, 64, v74
	global_store_short_d16_hi v50, v2, s[2:3]
	v_mul_f32_e32 v2, v34, v66
	v_bfe_u32 v34, v2, 16, 1
	v_add3_u32 v2, v2, v34, s46
	v_add_u32_e32 v34, 0x80, v74
	global_store_short_d16_hi v34, v2, s[2:3]
	v_mul_f32_e32 v2, v18, v66
	v_bfe_u32 v18, v2, 16, 1
	v_add3_u32 v2, v2, v18, s46
	v_rcp_f32_e32 v18, v67
	v_add_u32_e32 v34, 0xc0, v74
	global_store_short_d16_hi v34, v2, s[2:3]
	v_add_u32_e32 v2, 0x1000, v74
	v_mul_f32_e32 v3, v3, v18
	v_bfe_u32 v34, v3, 16, 1
	v_add3_u32 v3, v3, v34, s46
	global_store_short_d16_hi v2, v3, s[2:3]
	v_mul_f32_e32 v2, v51, v18
	v_bfe_u32 v3, v2, 16, 1
	v_add3_u32 v2, v2, v3, s46
	v_add_u32_e32 v3, 0x1040, v74
	global_store_short_d16_hi v3, v2, s[2:3]
	v_mul_f32_e32 v2, v35, v18
	v_bfe_u32 v3, v2, 16, 1
	v_add3_u32 v2, v2, v3, s46
	v_add_u32_e32 v3, 0x1080, v74
	global_store_short_d16_hi v3, v2, s[2:3]
	v_mul_f32_e32 v2, v19, v18
	v_bfe_u32 v3, v2, 16, 1
	v_add3_u32 v2, v2, v3, s46
	v_rcp_f32_e32 v3, v68
	v_add_u32_e32 v18, 0x10c0, v74
	global_store_short_d16_hi v18, v2, s[2:3]
	v_add_u32_e32 v2, 0x2000, v74
	v_mul_f32_e32 v4, v4, v3
	v_bfe_u32 v18, v4, 16, 1
	v_add3_u32 v4, v4, v18, s46
	global_store_short_d16_hi v2, v4, s[2:3]
	v_mul_f32_e32 v2, v52, v3
	v_bfe_u32 v4, v2, 16, 1
	v_add3_u32 v2, v2, v4, s46
	v_add_u32_e32 v4, 0x2040, v74
	global_store_short_d16_hi v4, v2, s[2:3]
	v_mul_f32_e32 v2, v36, v3
	v_bfe_u32 v4, v2, 16, 1
	v_add3_u32 v2, v2, v4, s46
	v_add_u32_e32 v4, 0x2080, v74
	global_store_short_d16_hi v4, v2, s[2:3]
	v_mul_f32_e32 v2, v20, v3
	v_bfe_u32 v3, v2, 16, 1
	v_add3_u32 v2, v2, v3, s46
	v_rcp_f32_e32 v3, v69
	v_add_u32_e32 v4, 0x20c0, v74
	global_store_short_d16_hi v4, v2, s[2:3]
	v_add_u32_e32 v2, 0x3000, v74
	v_mul_f32_e32 v4, v5, v3
	v_bfe_u32 v5, v4, 16, 1
	v_add3_u32 v4, v4, v5, s46
	global_store_short_d16_hi v2, v4, s[2:3]
	v_mul_f32_e32 v2, v53, v3
	v_bfe_u32 v4, v2, 16, 1
	v_add3_u32 v2, v2, v4, s46
	v_add_u32_e32 v4, 0x3040, v74
	global_store_short_d16_hi v4, v2, s[2:3]
	v_mul_f32_e32 v2, v37, v3
	v_bfe_u32 v4, v2, 16, 1
	v_add3_u32 v2, v2, v4, s46
	v_add_u32_e32 v4, 0x3080, v74
	global_store_short_d16_hi v4, v2, s[2:3]
	v_mul_f32_e32 v2, v21, v3
	v_bfe_u32 v3, v2, 16, 1
	v_add3_u32 v2, v2, v3, s46
	v_rcp_f32_e32 v3, v70
	v_add_u32_e32 v4, 0x30c0, v74
	global_store_short_d16_hi v4, v2, s[2:3]
	v_add_u32_e32 v2, 0x8000, v74
	v_mul_f32_e32 v4, v6, v3
	v_bfe_u32 v5, v4, 16, 1
	v_add3_u32 v4, v4, v5, s46
	global_store_short_d16_hi v2, v4, s[2:3]
	v_mul_f32_e32 v2, v54, v3
	v_bfe_u32 v4, v2, 16, 1
	v_add3_u32 v2, v2, v4, s46
	v_add_u32_e32 v4, 0x8040, v74
	global_store_short_d16_hi v4, v2, s[2:3]
	v_mul_f32_e32 v2, v38, v3
	v_bfe_u32 v4, v2, 16, 1
	v_add3_u32 v2, v2, v4, s46
	v_add_u32_e32 v4, 0x8080, v74
	global_store_short_d16_hi v4, v2, s[2:3]
	v_mul_f32_e32 v2, v22, v3
	v_bfe_u32 v3, v2, 16, 1
	v_add3_u32 v2, v2, v3, s46
	v_rcp_f32_e32 v3, v71
	v_add_u32_e32 v4, 0x80c0, v74
	global_store_short_d16_hi v4, v2, s[2:3]
	v_add_u32_e32 v2, 0x9000, v74
	v_mul_f32_e32 v4, v7, v3
	v_bfe_u32 v5, v4, 16, 1
	v_add3_u32 v4, v4, v5, s46
	global_store_short_d16_hi v2, v4, s[2:3]
	v_mul_f32_e32 v2, v55, v3
	v_bfe_u32 v4, v2, 16, 1
	v_add3_u32 v2, v2, v4, s46
	v_add_u32_e32 v4, 0x9040, v74
	global_store_short_d16_hi v4, v2, s[2:3]
	v_mul_f32_e32 v2, v39, v3
	v_bfe_u32 v4, v2, 16, 1
	v_add3_u32 v2, v2, v4, s46
	v_add_u32_e32 v4, 0x9080, v74
	global_store_short_d16_hi v4, v2, s[2:3]
	v_mul_f32_e32 v2, v23, v3
	v_bfe_u32 v3, v2, 16, 1
	v_add3_u32 v2, v2, v3, s46
	v_rcp_f32_e32 v3, v72
	v_add_u32_e32 v4, 0x90c0, v74
	global_store_short_d16_hi v4, v2, s[2:3]
	v_add_u32_e32 v2, 0xa000, v74
	v_mul_f32_e32 v4, v8, v3
	v_bfe_u32 v5, v4, 16, 1
	v_add3_u32 v4, v4, v5, s46
	global_store_short_d16_hi v2, v4, s[2:3]
	v_mul_f32_e32 v2, v56, v3
	v_bfe_u32 v4, v2, 16, 1
	v_add3_u32 v2, v2, v4, s46
	v_add_u32_e32 v4, 0xa040, v74
	global_store_short_d16_hi v4, v2, s[2:3]
	v_mul_f32_e32 v2, v40, v3
	v_bfe_u32 v4, v2, 16, 1
	v_add3_u32 v2, v2, v4, s46
	v_add_u32_e32 v4, 0xa080, v74
	v_rcp_f32_e32 v6, v73
	global_store_short_d16_hi v4, v2, s[2:3]
	v_mul_f32_e32 v2, v24, v3
	v_bfe_u32 v3, v2, 16, 1
	v_add3_u32 v2, v2, v3, s46
	v_add_u32_e32 v3, 0xa0c0, v74
	global_store_short_d16_hi v3, v2, s[2:3]
	v_mul_f32_e32 v3, v9, v6
	v_bfe_u32 v4, v3, 16, 1
	v_add_u32_e32 v2, 0xb000, v74
	v_add3_u32 v3, v3, v4, s46
	global_store_short_d16_hi v2, v3, s[2:3]
	v_mul_f32_e32 v2, v57, v6
	v_bfe_u32 v3, v2, 16, 1
	v_add3_u32 v2, v2, v3, s46
	v_add_u32_e32 v3, 0xb040, v74
	global_store_short_d16_hi v3, v2, s[2:3]
	v_mul_f32_e32 v2, v41, v6
	v_bfe_u32 v3, v2, 16, 1
	v_add3_u32 v2, v2, v3, s46
	v_add_u32_e32 v3, 0xb080, v74
	global_store_short_d16_hi v3, v2, s[2:3]
	ds_read_b128 v[2:5], v173 offset:64
	v_mul_f32_e32 v6, v25, v6
	v_bfe_u32 v7, v6, 16, 1
	v_add3_u32 v18, v6, v7, s46
	ds_read_b128 v[6:9], v173 offset:96
	s_waitcnt lgkmcnt(0)
	v_rcp_f32_e32 v2, v2
	v_add_u32_e32 v19, 0xb0c0, v74
	global_store_short_d16_hi v19, v18, s[2:3]
	v_add_u32_e32 v18, 0x10000, v74
	v_mul_f32_e32 v10, v10, v2
	v_bfe_u32 v19, v10, 16, 1
	v_add3_u32 v10, v10, v19, s46
	global_store_short_d16_hi v18, v10, s[2:3]
	v_mul_f32_e32 v10, v58, v2
	v_bfe_u32 v18, v10, 16, 1
	v_add3_u32 v10, v10, v18, s46
	v_add_u32_e32 v18, 0x10040, v74
	global_store_short_d16_hi v18, v10, s[2:3]
	v_mul_f32_e32 v10, v42, v2
	v_bfe_u32 v18, v10, 16, 1
	v_rcp_f32_e32 v3, v3
	v_add3_u32 v10, v10, v18, s46
	v_add_u32_e32 v18, 0x10080, v74
	v_mul_f32_e32 v2, v26, v2
	global_store_short_d16_hi v18, v10, s[2:3]
	v_bfe_u32 v10, v2, 16, 1
	v_add3_u32 v2, v2, v10, s46
	v_add_u32_e32 v10, 0x100c0, v74
	global_store_short_d16_hi v10, v2, s[2:3]
	v_mul_f32_e32 v10, v11, v3
	v_bfe_u32 v11, v10, 16, 1
	v_add_u32_e32 v2, 0x11000, v74
	v_add3_u32 v10, v10, v11, s46
	global_store_short_d16_hi v2, v10, s[2:3]
	v_mul_f32_e32 v2, v59, v3
	v_bfe_u32 v10, v2, 16, 1
	v_add3_u32 v2, v2, v10, s46
	v_add_u32_e32 v10, 0x11040, v74
	global_store_short_d16_hi v10, v2, s[2:3]
	v_mul_f32_e32 v2, v43, v3
	v_bfe_u32 v10, v2, 16, 1
	v_add3_u32 v2, v2, v10, s46
	v_add_u32_e32 v10, 0x11080, v74
	global_store_short_d16_hi v10, v2, s[2:3]
	v_mul_f32_e32 v2, v27, v3
	v_bfe_u32 v3, v2, 16, 1
	v_add3_u32 v2, v2, v3, s46
	v_rcp_f32_e32 v3, v4
	v_add_u32_e32 v4, 0x110c0, v74
	global_store_short_d16_hi v4, v2, s[2:3]
	v_add_u32_e32 v2, 0x12000, v74
	v_mul_f32_e32 v4, v12, v3
	v_bfe_u32 v10, v4, 16, 1
	v_add3_u32 v4, v4, v10, s46
	global_store_short_d16_hi v2, v4, s[2:3]
	v_mul_f32_e32 v2, v60, v3
	v_bfe_u32 v4, v2, 16, 1
	v_add3_u32 v2, v2, v4, s46
	v_add_u32_e32 v4, 0x12040, v74
	global_store_short_d16_hi v4, v2, s[2:3]
	v_mul_f32_e32 v2, v44, v3
	v_bfe_u32 v4, v2, 16, 1
	v_add3_u32 v2, v2, v4, s46
	v_add_u32_e32 v4, 0x12080, v74
	global_store_short_d16_hi v4, v2, s[2:3]
	v_mul_f32_e32 v2, v28, v3
	v_bfe_u32 v3, v2, 16, 1
	v_add3_u32 v2, v2, v3, s46
	v_rcp_f32_e32 v3, v5
	v_add_u32_e32 v4, 0x120c0, v74
	global_store_short_d16_hi v4, v2, s[2:3]
	v_add_u32_e32 v2, 0x13000, v74
	v_mul_f32_e32 v4, v13, v3
	v_bfe_u32 v5, v4, 16, 1
	v_add3_u32 v4, v4, v5, s46
	global_store_short_d16_hi v2, v4, s[2:3]
	v_mul_f32_e32 v2, v61, v3
	v_bfe_u32 v4, v2, 16, 1
	v_add3_u32 v2, v2, v4, s46
	v_add_u32_e32 v4, 0x13040, v74
	global_store_short_d16_hi v4, v2, s[2:3]
	v_mul_f32_e32 v2, v45, v3
	v_bfe_u32 v4, v2, 16, 1
	v_add3_u32 v2, v2, v4, s46
	v_add_u32_e32 v4, 0x13080, v74
	global_store_short_d16_hi v4, v2, s[2:3]
	v_mul_f32_e32 v2, v29, v3
	v_bfe_u32 v3, v2, 16, 1
	v_add3_u32 v2, v2, v3, s46
	v_rcp_f32_e32 v3, v6
	v_add_u32_e32 v4, 0x130c0, v74
	global_store_short_d16_hi v4, v2, s[2:3]
	v_add_u32_e32 v2, 0x18000, v74
	v_mul_f32_e32 v4, v14, v3
	v_bfe_u32 v5, v4, 16, 1
	v_add3_u32 v4, v4, v5, s46
	global_store_short_d16_hi v2, v4, s[2:3]
	v_mul_f32_e32 v2, v62, v3
	v_bfe_u32 v4, v2, 16, 1
	v_add3_u32 v2, v2, v4, s46
	v_add_u32_e32 v4, 0x18040, v74
	global_store_short_d16_hi v4, v2, s[2:3]
	v_mul_f32_e32 v2, v46, v3
	v_bfe_u32 v4, v2, 16, 1
	v_add3_u32 v2, v2, v4, s46
	v_add_u32_e32 v4, 0x18080, v74
	global_store_short_d16_hi v4, v2, s[2:3]
	v_mul_f32_e32 v2, v30, v3
	v_bfe_u32 v3, v2, 16, 1
	v_add3_u32 v2, v2, v3, s46
	v_rcp_f32_e32 v3, v7
	v_add_u32_e32 v4, 0x180c0, v74
	global_store_short_d16_hi v4, v2, s[2:3]
	v_add_u32_e32 v2, 0x19000, v74
	v_mul_f32_e32 v4, v15, v3
	v_bfe_u32 v5, v4, 16, 1
	v_add3_u32 v4, v4, v5, s46
	global_store_short_d16_hi v2, v4, s[2:3]
	v_mul_f32_e32 v2, v63, v3
	v_bfe_u32 v4, v2, 16, 1
	v_add3_u32 v2, v2, v4, s46
	v_add_u32_e32 v4, 0x19040, v74
	global_store_short_d16_hi v4, v2, s[2:3]
	v_mul_f32_e32 v2, v47, v3
	v_bfe_u32 v4, v2, 16, 1
	v_add3_u32 v2, v2, v4, s46
	v_add_u32_e32 v4, 0x19080, v74
	global_store_short_d16_hi v4, v2, s[2:3]
	v_mul_f32_e32 v2, v31, v3
	v_bfe_u32 v3, v2, 16, 1
	v_add3_u32 v2, v2, v3, s46
	v_rcp_f32_e32 v3, v8
	v_add_u32_e32 v4, 0x190c0, v74
	global_store_short_d16_hi v4, v2, s[2:3]
	v_add_u32_e32 v2, 0x1a000, v74
	v_mul_f32_e32 v4, v16, v3
	v_bfe_u32 v5, v4, 16, 1
	v_add3_u32 v4, v4, v5, s46
	global_store_short_d16_hi v2, v4, s[2:3]
	v_mul_f32_e32 v2, v64, v3
	v_bfe_u32 v4, v2, 16, 1
	v_add3_u32 v2, v2, v4, s46
	v_add_u32_e32 v4, 0x1a040, v74
	global_store_short_d16_hi v4, v2, s[2:3]
	v_mul_f32_e32 v2, v48, v3
	v_bfe_u32 v4, v2, 16, 1
	v_add3_u32 v2, v2, v4, s46
	v_add_u32_e32 v4, 0x1a080, v74
	global_store_short_d16_hi v4, v2, s[2:3]
	v_mul_f32_e32 v2, v32, v3
	v_bfe_u32 v3, v2, 16, 1
	v_add3_u32 v2, v2, v3, s46
	v_rcp_f32_e32 v3, v9
	v_add_u32_e32 v4, 0x1a0c0, v74
	global_store_short_d16_hi v4, v2, s[2:3]
	v_add_u32_e32 v2, 0x1b000, v74
	v_mul_f32_e32 v4, v17, v3
	v_bfe_u32 v5, v4, 16, 1
	v_add3_u32 v4, v4, v5, s46
	global_store_short_d16_hi v2, v4, s[2:3]
	v_mul_f32_e32 v2, v65, v3
	v_bfe_u32 v4, v2, 16, 1
	v_add3_u32 v2, v2, v4, s46
	v_add_u32_e32 v4, 0x1b040, v74
	global_store_short_d16_hi v4, v2, s[2:3]
	v_mul_f32_e32 v2, v49, v3
	v_bfe_u32 v4, v2, 16, 1
	v_add3_u32 v2, v2, v4, s46
	v_add_u32_e32 v4, 0x1b080, v74
	global_store_short_d16_hi v4, v2, s[2:3]
	v_mul_f32_e32 v2, v33, v3
	v_bfe_u32 v3, v2, 16, 1
	v_add3_u32 v2, v2, v3, s46
	v_add_u32_e32 v3, 0x1b0c0, v74
	global_store_short_d16_hi v3, v2, s[2:3]
	s_waitcnt lgkmcnt(0)
	s_add_i32 s47, s47, s96
	s_cmpk_lt_i32 s47, 0x200
	s_nop 0
	s_barrier
	s_cbranch_scc0 .LBB0_1589

.LBB0_1590:
	s_or_b64 exec, exec, s[2:3]
	v_mov_b32_e32 v74, v166
	s_waitcnt lgkmcnt(0)
	ds_read_b128 v[66:69], v173
	ds_read_b128 v[70:73], v173 offset:32
	s_lshl_b64 s[2:3], s[22:23], 12
	s_add_u32 s2, s38, s2
	s_addc_u32 s3, s39, s3
	s_waitcnt lgkmcnt(0)
	v_rcp_f32_e32 v66, v66
	s_lshl_b32 s22, s46, 1
	s_add_u32 s2, s2, s22
	s_addc_u32 s3, s3, 0
	v_mul_f32_e32 v2, v2, v66
	v_bfe_u32 v75, v2, 16, 1
	v_lshlrev_b32_e32 v74, 1, v74
	v_add3_u32 v2, v2, v75, s43
	global_store_short_d16_hi v74, v2, s[2:3]
	v_mul_f32_e32 v2, v50, v66
	v_bfe_u32 v50, v2, 16, 1
	v_add3_u32 v2, v2, v50, s43
	v_add_u32_e32 v50, 64, v74
	global_store_short_d16_hi v50, v2, s[2:3]
	v_mul_f32_e32 v2, v34, v66
	v_bfe_u32 v34, v2, 16, 1
	v_add3_u32 v2, v2, v34, s43
	v_add_u32_e32 v34, 0x80, v74
	global_store_short_d16_hi v34, v2, s[2:3]
	v_mul_f32_e32 v2, v18, v66
	v_bfe_u32 v18, v2, 16, 1
	v_add3_u32 v2, v2, v18, s43
	v_rcp_f32_e32 v18, v67
	v_add_u32_e32 v34, 0xc0, v74
	global_store_short_d16_hi v34, v2, s[2:3]
	v_add_u32_e32 v2, 0x1000, v74
	v_mul_f32_e32 v3, v3, v18
	v_bfe_u32 v34, v3, 16, 1
	v_add3_u32 v3, v3, v34, s43
	global_store_short_d16_hi v2, v3, s[2:3]
	v_mul_f32_e32 v2, v51, v18
	v_bfe_u32 v3, v2, 16, 1
	v_add3_u32 v2, v2, v3, s43
	v_add_u32_e32 v3, 0x1040, v74
	global_store_short_d16_hi v3, v2, s[2:3]
	v_mul_f32_e32 v2, v35, v18
	v_bfe_u32 v3, v2, 16, 1
	v_add3_u32 v2, v2, v3, s43
	v_add_u32_e32 v3, 0x1080, v74
	global_store_short_d16_hi v3, v2, s[2:3]
	v_mul_f32_e32 v2, v19, v18
	v_bfe_u32 v3, v2, 16, 1
	v_add3_u32 v2, v2, v3, s43
	v_rcp_f32_e32 v3, v68
	v_add_u32_e32 v18, 0x10c0, v74
	global_store_short_d16_hi v18, v2, s[2:3]
	v_add_u32_e32 v2, 0x2000, v74
	v_mul_f32_e32 v4, v4, v3
	v_bfe_u32 v18, v4, 16, 1
	v_add3_u32 v4, v4, v18, s43
	global_store_short_d16_hi v2, v4, s[2:3]
	v_mul_f32_e32 v2, v52, v3
	v_bfe_u32 v4, v2, 16, 1
	v_add3_u32 v2, v2, v4, s43
	v_add_u32_e32 v4, 0x2040, v74
	global_store_short_d16_hi v4, v2, s[2:3]
	v_mul_f32_e32 v2, v36, v3
	v_bfe_u32 v4, v2, 16, 1
	v_add3_u32 v2, v2, v4, s43
	v_add_u32_e32 v4, 0x2080, v74
	global_store_short_d16_hi v4, v2, s[2:3]
	v_mul_f32_e32 v2, v20, v3
	v_bfe_u32 v3, v2, 16, 1
	v_add3_u32 v2, v2, v3, s43
	v_rcp_f32_e32 v3, v69
	v_add_u32_e32 v4, 0x20c0, v74
	global_store_short_d16_hi v4, v2, s[2:3]
	v_add_u32_e32 v2, 0x3000, v74
	v_mul_f32_e32 v4, v5, v3
	v_bfe_u32 v5, v4, 16, 1
	v_add3_u32 v4, v4, v5, s43
	global_store_short_d16_hi v2, v4, s[2:3]
	v_mul_f32_e32 v2, v53, v3
	v_bfe_u32 v4, v2, 16, 1
	v_add3_u32 v2, v2, v4, s43
	v_add_u32_e32 v4, 0x3040, v74
	global_store_short_d16_hi v4, v2, s[2:3]
	v_mul_f32_e32 v2, v37, v3
	v_bfe_u32 v4, v2, 16, 1
	v_add3_u32 v2, v2, v4, s43
	v_add_u32_e32 v4, 0x3080, v74
	global_store_short_d16_hi v4, v2, s[2:3]
	v_mul_f32_e32 v2, v21, v3
	v_bfe_u32 v3, v2, 16, 1
	v_add3_u32 v2, v2, v3, s43
	v_rcp_f32_e32 v3, v70
	v_add_u32_e32 v4, 0x30c0, v74
	global_store_short_d16_hi v4, v2, s[2:3]
	v_add_u32_e32 v2, 0x8000, v74
	v_mul_f32_e32 v4, v6, v3
	v_bfe_u32 v5, v4, 16, 1
	v_add3_u32 v4, v4, v5, s43
	global_store_short_d16_hi v2, v4, s[2:3]
	v_mul_f32_e32 v2, v54, v3
	v_bfe_u32 v4, v2, 16, 1
	v_add3_u32 v2, v2, v4, s43
	v_add_u32_e32 v4, 0x8040, v74
	global_store_short_d16_hi v4, v2, s[2:3]
	v_mul_f32_e32 v2, v38, v3
	v_bfe_u32 v4, v2, 16, 1
	v_add3_u32 v2, v2, v4, s43
	v_add_u32_e32 v4, 0x8080, v74
	global_store_short_d16_hi v4, v2, s[2:3]
	v_mul_f32_e32 v2, v22, v3
	v_bfe_u32 v3, v2, 16, 1
	v_add3_u32 v2, v2, v3, s43
	v_rcp_f32_e32 v3, v71
	v_add_u32_e32 v4, 0x80c0, v74
	global_store_short_d16_hi v4, v2, s[2:3]
	v_add_u32_e32 v2, 0x9000, v74
	v_mul_f32_e32 v4, v7, v3
	v_bfe_u32 v5, v4, 16, 1
	v_add3_u32 v4, v4, v5, s43
	global_store_short_d16_hi v2, v4, s[2:3]
	v_mul_f32_e32 v2, v55, v3
	v_bfe_u32 v4, v2, 16, 1
	v_add3_u32 v2, v2, v4, s43
	v_add_u32_e32 v4, 0x9040, v74
	global_store_short_d16_hi v4, v2, s[2:3]
	v_mul_f32_e32 v2, v39, v3
	v_bfe_u32 v4, v2, 16, 1
	v_add3_u32 v2, v2, v4, s43
	v_add_u32_e32 v4, 0x9080, v74
	global_store_short_d16_hi v4, v2, s[2:3]
	v_mul_f32_e32 v2, v23, v3
	v_bfe_u32 v3, v2, 16, 1
	v_add3_u32 v2, v2, v3, s43
	v_rcp_f32_e32 v3, v72
	v_add_u32_e32 v4, 0x90c0, v74
	global_store_short_d16_hi v4, v2, s[2:3]
	v_add_u32_e32 v2, 0xa000, v74
	v_mul_f32_e32 v4, v8, v3
	v_bfe_u32 v5, v4, 16, 1
	v_add3_u32 v4, v4, v5, s43
	global_store_short_d16_hi v2, v4, s[2:3]
	v_mul_f32_e32 v2, v56, v3
	v_bfe_u32 v4, v2, 16, 1
	v_add3_u32 v2, v2, v4, s43
	v_add_u32_e32 v4, 0xa040, v74
	global_store_short_d16_hi v4, v2, s[2:3]
	v_mul_f32_e32 v2, v40, v3
	v_bfe_u32 v4, v2, 16, 1
	v_add3_u32 v2, v2, v4, s43
	v_add_u32_e32 v4, 0xa080, v74
	v_rcp_f32_e32 v6, v73
	global_store_short_d16_hi v4, v2, s[2:3]
	v_mul_f32_e32 v2, v24, v3
	v_bfe_u32 v3, v2, 16, 1
	v_add3_u32 v2, v2, v3, s43
	v_add_u32_e32 v3, 0xa0c0, v74
	global_store_short_d16_hi v3, v2, s[2:3]
	v_mul_f32_e32 v3, v9, v6
	v_bfe_u32 v4, v3, 16, 1
	v_add_u32_e32 v2, 0xb000, v74
	v_add3_u32 v3, v3, v4, s43
	global_store_short_d16_hi v2, v3, s[2:3]
	v_mul_f32_e32 v2, v57, v6
	v_bfe_u32 v3, v2, 16, 1
	v_add3_u32 v2, v2, v3, s43
	v_add_u32_e32 v3, 0xb040, v74
	global_store_short_d16_hi v3, v2, s[2:3]
	v_mul_f32_e32 v2, v41, v6
	v_bfe_u32 v3, v2, 16, 1
	v_add3_u32 v2, v2, v3, s43
	v_add_u32_e32 v3, 0xb080, v74
	global_store_short_d16_hi v3, v2, s[2:3]
	ds_read_b128 v[2:5], v173 offset:64
	v_mul_f32_e32 v6, v25, v6
	v_bfe_u32 v7, v6, 16, 1
	v_add3_u32 v18, v6, v7, s43
	ds_read_b128 v[6:9], v173 offset:96
	s_waitcnt lgkmcnt(0)
	v_rcp_f32_e32 v2, v2
	v_add_u32_e32 v19, 0xb0c0, v74
	global_store_short_d16_hi v19, v18, s[2:3]
	v_add_u32_e32 v18, 0x10000, v74
	v_mul_f32_e32 v10, v10, v2
	v_bfe_u32 v19, v10, 16, 1
	v_add3_u32 v10, v10, v19, s43
	global_store_short_d16_hi v18, v10, s[2:3]
	v_mul_f32_e32 v10, v58, v2
	v_bfe_u32 v18, v10, 16, 1
	v_add3_u32 v10, v10, v18, s43
	v_add_u32_e32 v18, 0x10040, v74
	global_store_short_d16_hi v18, v10, s[2:3]
	v_mul_f32_e32 v10, v42, v2
	v_bfe_u32 v18, v10, 16, 1
	v_rcp_f32_e32 v3, v3
	v_add3_u32 v10, v10, v18, s43
	v_add_u32_e32 v18, 0x10080, v74
	v_mul_f32_e32 v2, v26, v2
	global_store_short_d16_hi v18, v10, s[2:3]
	v_bfe_u32 v10, v2, 16, 1
	v_add3_u32 v2, v2, v10, s43
	v_add_u32_e32 v10, 0x100c0, v74
	global_store_short_d16_hi v10, v2, s[2:3]
	v_mul_f32_e32 v10, v11, v3
	v_bfe_u32 v11, v10, 16, 1
	v_add_u32_e32 v2, 0x11000, v74
	v_add3_u32 v10, v10, v11, s43
	global_store_short_d16_hi v2, v10, s[2:3]
	v_mul_f32_e32 v2, v59, v3
	v_bfe_u32 v10, v2, 16, 1
	v_add3_u32 v2, v2, v10, s43
	v_add_u32_e32 v10, 0x11040, v74
	global_store_short_d16_hi v10, v2, s[2:3]
	v_mul_f32_e32 v2, v43, v3
	v_bfe_u32 v10, v2, 16, 1
	v_add3_u32 v2, v2, v10, s43
	v_add_u32_e32 v10, 0x11080, v74
	global_store_short_d16_hi v10, v2, s[2:3]
	v_mul_f32_e32 v2, v27, v3
	v_bfe_u32 v3, v2, 16, 1
	v_add3_u32 v2, v2, v3, s43
	v_rcp_f32_e32 v3, v4
	v_add_u32_e32 v4, 0x110c0, v74
	global_store_short_d16_hi v4, v2, s[2:3]
	v_add_u32_e32 v2, 0x12000, v74
	v_mul_f32_e32 v4, v12, v3
	v_bfe_u32 v10, v4, 16, 1
	v_add3_u32 v4, v4, v10, s43
	global_store_short_d16_hi v2, v4, s[2:3]
	v_mul_f32_e32 v2, v60, v3
	v_bfe_u32 v4, v2, 16, 1
	v_add3_u32 v2, v2, v4, s43
	v_add_u32_e32 v4, 0x12040, v74
	global_store_short_d16_hi v4, v2, s[2:3]
	v_mul_f32_e32 v2, v44, v3
	v_bfe_u32 v4, v2, 16, 1
	v_add3_u32 v2, v2, v4, s43
	v_add_u32_e32 v4, 0x12080, v74
	global_store_short_d16_hi v4, v2, s[2:3]
	v_mul_f32_e32 v2, v28, v3
	v_bfe_u32 v3, v2, 16, 1
	v_add3_u32 v2, v2, v3, s43
	v_rcp_f32_e32 v3, v5
	v_add_u32_e32 v4, 0x120c0, v74
	global_store_short_d16_hi v4, v2, s[2:3]
	v_add_u32_e32 v2, 0x13000, v74
	v_mul_f32_e32 v4, v13, v3
	v_bfe_u32 v5, v4, 16, 1
	v_add3_u32 v4, v4, v5, s43
	global_store_short_d16_hi v2, v4, s[2:3]
	v_mul_f32_e32 v2, v61, v3
	v_bfe_u32 v4, v2, 16, 1
	v_add3_u32 v2, v2, v4, s43
	v_add_u32_e32 v4, 0x13040, v74
	global_store_short_d16_hi v4, v2, s[2:3]
	v_mul_f32_e32 v2, v45, v3
	v_bfe_u32 v4, v2, 16, 1
	v_add3_u32 v2, v2, v4, s43
	v_add_u32_e32 v4, 0x13080, v74
	global_store_short_d16_hi v4, v2, s[2:3]
	v_mul_f32_e32 v2, v29, v3
	v_bfe_u32 v3, v2, 16, 1
	v_add3_u32 v2, v2, v3, s43
	v_rcp_f32_e32 v3, v6
	v_add_u32_e32 v4, 0x130c0, v74
	global_store_short_d16_hi v4, v2, s[2:3]
	v_add_u32_e32 v2, 0x18000, v74
	v_mul_f32_e32 v4, v14, v3
	v_bfe_u32 v5, v4, 16, 1
	v_add3_u32 v4, v4, v5, s43
	global_store_short_d16_hi v2, v4, s[2:3]
	v_mul_f32_e32 v2, v62, v3
	v_bfe_u32 v4, v2, 16, 1
	v_add3_u32 v2, v2, v4, s43
	v_add_u32_e32 v4, 0x18040, v74
	global_store_short_d16_hi v4, v2, s[2:3]
	v_mul_f32_e32 v2, v46, v3
	v_bfe_u32 v4, v2, 16, 1
	v_add3_u32 v2, v2, v4, s43
	v_add_u32_e32 v4, 0x18080, v74
	global_store_short_d16_hi v4, v2, s[2:3]
	v_mul_f32_e32 v2, v30, v3
	v_bfe_u32 v3, v2, 16, 1
	v_add3_u32 v2, v2, v3, s43
	v_rcp_f32_e32 v3, v7
	v_add_u32_e32 v4, 0x180c0, v74
	global_store_short_d16_hi v4, v2, s[2:3]
	v_add_u32_e32 v2, 0x19000, v74
	v_mul_f32_e32 v4, v15, v3
	v_bfe_u32 v5, v4, 16, 1
	v_add3_u32 v4, v4, v5, s43
	global_store_short_d16_hi v2, v4, s[2:3]
	v_mul_f32_e32 v2, v63, v3
	v_bfe_u32 v4, v2, 16, 1
	v_add3_u32 v2, v2, v4, s43
	v_add_u32_e32 v4, 0x19040, v74
	global_store_short_d16_hi v4, v2, s[2:3]
	v_mul_f32_e32 v2, v47, v3
	v_bfe_u32 v4, v2, 16, 1
	v_add3_u32 v2, v2, v4, s43
	v_add_u32_e32 v4, 0x19080, v74
	global_store_short_d16_hi v4, v2, s[2:3]
	v_mul_f32_e32 v2, v31, v3
	v_bfe_u32 v3, v2, 16, 1
	v_add3_u32 v2, v2, v3, s43
	v_rcp_f32_e32 v3, v8
	v_add_u32_e32 v4, 0x190c0, v74
	global_store_short_d16_hi v4, v2, s[2:3]
	v_add_u32_e32 v2, 0x1a000, v74
	v_mul_f32_e32 v4, v16, v3
	v_bfe_u32 v5, v4, 16, 1
	v_add3_u32 v4, v4, v5, s43
	global_store_short_d16_hi v2, v4, s[2:3]
	v_mul_f32_e32 v2, v64, v3
	v_bfe_u32 v4, v2, 16, 1
	v_add3_u32 v2, v2, v4, s43
	v_add_u32_e32 v4, 0x1a040, v74
	global_store_short_d16_hi v4, v2, s[2:3]
	v_mul_f32_e32 v2, v48, v3
	v_bfe_u32 v4, v2, 16, 1
	v_add3_u32 v2, v2, v4, s43
	v_add_u32_e32 v4, 0x1a080, v74
	global_store_short_d16_hi v4, v2, s[2:3]
	v_mul_f32_e32 v2, v32, v3
	v_bfe_u32 v3, v2, 16, 1
	v_add3_u32 v2, v2, v3, s43
	v_rcp_f32_e32 v3, v9
	v_add_u32_e32 v4, 0x1a0c0, v74
	global_store_short_d16_hi v4, v2, s[2:3]
	v_add_u32_e32 v2, 0x1b000, v74
	v_mul_f32_e32 v4, v17, v3
	v_bfe_u32 v5, v4, 16, 1
	v_add3_u32 v4, v4, v5, s43
	global_store_short_d16_hi v2, v4, s[2:3]
	v_mul_f32_e32 v2, v65, v3
	v_bfe_u32 v4, v2, 16, 1
	v_add3_u32 v2, v2, v4, s43
	v_add_u32_e32 v4, 0x1b040, v74
	global_store_short_d16_hi v4, v2, s[2:3]
	v_mul_f32_e32 v2, v49, v3
	v_bfe_u32 v4, v2, 16, 1
	v_add3_u32 v2, v2, v4, s43
	v_add_u32_e32 v4, 0x1b080, v74
	global_store_short_d16_hi v4, v2, s[2:3]
	v_mul_f32_e32 v2, v33, v3
	v_bfe_u32 v3, v2, 16, 1
	v_add3_u32 v2, v2, v3, s43
	v_add_u32_e32 v3, 0x1b0c0, v74
	global_store_short_d16_hi v3, v2, s[2:3]
	s_waitcnt lgkmcnt(0)
	s_add_i32 s45, s45, s96
	s_add_i32 s26, s26, s27
	s_add_i32 s44, s44, s96
	s_cmpk_lt_i32 s45, 0x200
	s_nop 0
	s_barrier
	s_cbranch_scc0 .LBB0_1605

.LBB0_3419:
	s_or_b64 exec, exec, s[12:13]
	v_mov_b32_e32 v3, v150
	s_waitcnt lgkmcnt(0)
	ds_read_b128 v[68:71], v154
	ds_read_b128 v[72:75], v154 offset:32
	s_lshl_b64 s[2:3], s[2:3], 1
	s_add_u32 s2, s34, s2
	s_addc_u32 s3, s35, s3
	s_waitcnt lgkmcnt(0)
	v_rcp_f32_e32 v68, v68
	s_lshl_b32 s12, s14, 1
	s_add_u32 s2, s2, s12
	s_addc_u32 s3, s3, 0
	v_mul_f32_e32 v52, v52, v68
	v_bfe_u32 v76, v52, 16, 1
	v_lshlrev_b32_e32 v3, 1, v3
	v_add3_u32 v52, v52, v76, s41
	v_mul_f32_e32 v36, v36, v68
	global_store_short_d16_hi v3, v52, s[2:3]
	v_bfe_u32 v52, v36, 16, 1
	v_add3_u32 v36, v36, v52, s41
	v_add_u32_e32 v52, 64, v3
	v_mul_f32_e32 v20, v20, v68
	global_store_short_d16_hi v52, v36, s[2:3]
	v_bfe_u32 v36, v20, 16, 1
	v_add3_u32 v20, v20, v36, s41
	v_add_u32_e32 v36, 0x80, v3
	v_mul_f32_e32 v4, v4, v68
	global_store_short_d16_hi v36, v20, s[2:3]
	v_bfe_u32 v20, v4, 16, 1
	v_add3_u32 v4, v4, v20, s41
	v_rcp_f32_e32 v20, v69
	v_add_u32_e32 v36, 0xc0, v3
	global_store_short_d16_hi v36, v4, s[2:3]
	v_add_u32_e32 v4, 0x1000, v3
	v_mul_f32_e32 v36, v53, v20
	v_bfe_u32 v52, v36, 16, 1
	v_add3_u32 v36, v36, v52, s41
	global_store_short_d16_hi v4, v36, s[2:3]
	v_mul_f32_e32 v4, v37, v20
	v_bfe_u32 v36, v4, 16, 1
	v_add3_u32 v4, v4, v36, s41
	v_add_u32_e32 v36, 0x1040, v3
	global_store_short_d16_hi v36, v4, s[2:3]
	v_mul_f32_e32 v4, v21, v20
	v_bfe_u32 v21, v4, 16, 1
	v_add3_u32 v4, v4, v21, s41
	v_add_u32_e32 v21, 0x1080, v3
	global_store_short_d16_hi v21, v4, s[2:3]
	v_mul_f32_e32 v4, v5, v20
	v_bfe_u32 v5, v4, 16, 1
	v_add3_u32 v4, v4, v5, s41
	v_rcp_f32_e32 v5, v70
	v_add_u32_e32 v20, 0x10c0, v3
	global_store_short_d16_hi v20, v4, s[2:3]
	v_add_u32_e32 v4, 0x2000, v3
	v_mul_f32_e32 v20, v54, v5
	v_bfe_u32 v21, v20, 16, 1
	v_add3_u32 v20, v20, v21, s41
	global_store_short_d16_hi v4, v20, s[2:3]
	v_mul_f32_e32 v4, v38, v5
	v_bfe_u32 v20, v4, 16, 1
	v_add3_u32 v4, v4, v20, s41
	v_add_u32_e32 v20, 0x2040, v3
	global_store_short_d16_hi v20, v4, s[2:3]
	v_mul_f32_e32 v4, v22, v5
	v_bfe_u32 v20, v4, 16, 1
	v_add3_u32 v4, v4, v20, s41
	v_add_u32_e32 v20, 0x2080, v3
	global_store_short_d16_hi v20, v4, s[2:3]
	v_mul_f32_e32 v4, v6, v5
	v_bfe_u32 v5, v4, 16, 1
	v_add3_u32 v4, v4, v5, s41
	v_rcp_f32_e32 v5, v71
	v_add_u32_e32 v6, 0x20c0, v3
	global_store_short_d16_hi v6, v4, s[2:3]
	v_add_u32_e32 v4, 0x3000, v3
	v_mul_f32_e32 v6, v55, v5
	v_bfe_u32 v20, v6, 16, 1
	v_add3_u32 v6, v6, v20, s41
	global_store_short_d16_hi v4, v6, s[2:3]
	v_mul_f32_e32 v4, v39, v5
	v_bfe_u32 v6, v4, 16, 1
	v_add3_u32 v4, v4, v6, s41
	v_add_u32_e32 v6, 0x3040, v3
	global_store_short_d16_hi v6, v4, s[2:3]
	v_mul_f32_e32 v4, v23, v5
	v_bfe_u32 v6, v4, 16, 1
	v_add3_u32 v4, v4, v6, s41
	v_add_u32_e32 v6, 0x3080, v3
	global_store_short_d16_hi v6, v4, s[2:3]
	v_mul_f32_e32 v4, v7, v5
	v_bfe_u32 v5, v4, 16, 1
	v_add3_u32 v4, v4, v5, s41
	v_rcp_f32_e32 v5, v72
	v_add_u32_e32 v6, 0x30c0, v3
	global_store_short_d16_hi v6, v4, s[2:3]
	v_add_u32_e32 v4, 0x8000, v3
	v_mul_f32_e32 v6, v56, v5
	v_bfe_u32 v7, v6, 16, 1
	v_add3_u32 v6, v6, v7, s41
	global_store_short_d16_hi v4, v6, s[2:3]
	v_mul_f32_e32 v4, v40, v5
	v_bfe_u32 v6, v4, 16, 1
	v_add3_u32 v4, v4, v6, s41
	v_add_u32_e32 v6, 0x8040, v3
	global_store_short_d16_hi v6, v4, s[2:3]
	v_mul_f32_e32 v4, v24, v5
	v_bfe_u32 v6, v4, 16, 1
	v_add3_u32 v4, v4, v6, s41
	v_add_u32_e32 v6, 0x8080, v3
	global_store_short_d16_hi v6, v4, s[2:3]
	v_mul_f32_e32 v4, v8, v5
	v_bfe_u32 v5, v4, 16, 1
	v_add3_u32 v4, v4, v5, s41
	v_rcp_f32_e32 v5, v73
	v_add_u32_e32 v6, 0x80c0, v3
	global_store_short_d16_hi v6, v4, s[2:3]
	v_add_u32_e32 v4, 0x9000, v3
	v_mul_f32_e32 v6, v57, v5
	v_bfe_u32 v7, v6, 16, 1
	v_add3_u32 v6, v6, v7, s41
	global_store_short_d16_hi v4, v6, s[2:3]
	v_mul_f32_e32 v4, v41, v5
	v_bfe_u32 v6, v4, 16, 1
	v_add3_u32 v4, v4, v6, s41
	v_add_u32_e32 v6, 0x9040, v3
	global_store_short_d16_hi v6, v4, s[2:3]
	v_mul_f32_e32 v4, v25, v5
	v_bfe_u32 v6, v4, 16, 1
	v_add3_u32 v4, v4, v6, s41
	v_add_u32_e32 v6, 0x9080, v3
	global_store_short_d16_hi v6, v4, s[2:3]
	v_mul_f32_e32 v4, v9, v5
	v_bfe_u32 v5, v4, 16, 1
	v_add3_u32 v4, v4, v5, s41
	v_rcp_f32_e32 v5, v74
	v_add_u32_e32 v6, 0x90c0, v3
	global_store_short_d16_hi v6, v4, s[2:3]
	v_add_u32_e32 v4, 0xa000, v3
	v_mul_f32_e32 v6, v58, v5
	v_bfe_u32 v7, v6, 16, 1
	v_add3_u32 v6, v6, v7, s41
	global_store_short_d16_hi v4, v6, s[2:3]
	v_mul_f32_e32 v4, v42, v5
	v_bfe_u32 v6, v4, 16, 1
	v_add3_u32 v4, v4, v6, s41
	v_add_u32_e32 v6, 0xa040, v3
	global_store_short_d16_hi v6, v4, s[2:3]
	v_mul_f32_e32 v4, v26, v5
	v_bfe_u32 v6, v4, 16, 1
	v_add3_u32 v4, v4, v6, s41
	v_add_u32_e32 v6, 0xa080, v3
	v_rcp_f32_e32 v8, v75
	global_store_short_d16_hi v6, v4, s[2:3]
	v_mul_f32_e32 v4, v10, v5
	v_bfe_u32 v5, v4, 16, 1
	v_add3_u32 v4, v4, v5, s41
	v_add_u32_e32 v5, 0xa0c0, v3
	global_store_short_d16_hi v5, v4, s[2:3]
	v_mul_f32_e32 v5, v59, v8
	v_bfe_u32 v6, v5, 16, 1
	v_add_u32_e32 v4, 0xb000, v3
	v_add3_u32 v5, v5, v6, s41
	global_store_short_d16_hi v4, v5, s[2:3]
	v_mul_f32_e32 v4, v43, v8
	v_bfe_u32 v5, v4, 16, 1
	v_add3_u32 v4, v4, v5, s41
	v_add_u32_e32 v5, 0xb040, v3
	global_store_short_d16_hi v5, v4, s[2:3]
	v_mul_f32_e32 v4, v27, v8
	v_bfe_u32 v5, v4, 16, 1
	v_add3_u32 v4, v4, v5, s41
	v_add_u32_e32 v5, 0xb080, v3
	global_store_short_d16_hi v5, v4, s[2:3]
	ds_read_b128 v[4:7], v154 offset:64
	v_mul_f32_e32 v8, v11, v8
	v_bfe_u32 v9, v8, 16, 1
	v_add3_u32 v20, v8, v9, s41
	ds_read_b128 v[8:11], v154 offset:96
	s_waitcnt lgkmcnt(0)
	v_rcp_f32_e32 v4, v4
	v_add_u32_e32 v21, 0xb0c0, v3
	global_store_short_d16_hi v21, v20, s[2:3]
	v_add_u32_e32 v20, 0x10000, v3
	v_mul_f32_e32 v21, v60, v4
	v_bfe_u32 v22, v21, 16, 1
	v_add3_u32 v21, v21, v22, s41
	global_store_short_d16_hi v20, v21, s[2:3]
	v_mul_f32_e32 v20, v44, v4
	v_bfe_u32 v21, v20, 16, 1
	v_add3_u32 v20, v20, v21, s41
	v_add_u32_e32 v21, 0x10040, v3
	v_rcp_f32_e32 v5, v5
	global_store_short_d16_hi v21, v20, s[2:3]
	v_mul_f32_e32 v20, v28, v4
	v_mul_f32_e32 v4, v12, v4
	v_bfe_u32 v12, v4, 16, 1
	v_bfe_u32 v21, v20, 16, 1
	v_add3_u32 v4, v4, v12, s41
	v_add_u32_e32 v12, 0x100c0, v3
	v_add3_u32 v20, v20, v21, s41
	v_add_u32_e32 v21, 0x10080, v3
	global_store_short_d16_hi v12, v4, s[2:3]
	v_mul_f32_e32 v12, v61, v5
	global_store_short_d16_hi v21, v20, s[2:3]
	v_bfe_u32 v20, v12, 16, 1
	v_add_u32_e32 v4, 0x11000, v3
	v_add3_u32 v12, v12, v20, s41
	global_store_short_d16_hi v4, v12, s[2:3]
	v_mul_f32_e32 v4, v45, v5
	v_bfe_u32 v12, v4, 16, 1
	v_add3_u32 v4, v4, v12, s41
	v_add_u32_e32 v12, 0x11040, v3
	global_store_short_d16_hi v12, v4, s[2:3]
	v_mul_f32_e32 v4, v29, v5
	v_bfe_u32 v12, v4, 16, 1
	v_add3_u32 v4, v4, v12, s41
	v_add_u32_e32 v12, 0x11080, v3
	global_store_short_d16_hi v12, v4, s[2:3]
	v_mul_f32_e32 v4, v13, v5
	v_bfe_u32 v5, v4, 16, 1
	v_add3_u32 v4, v4, v5, s41
	v_rcp_f32_e32 v5, v6
	v_add_u32_e32 v6, 0x110c0, v3
	global_store_short_d16_hi v6, v4, s[2:3]
	v_add_u32_e32 v4, 0x12000, v3
	v_mul_f32_e32 v6, v62, v5
	v_bfe_u32 v12, v6, 16, 1
	v_add3_u32 v6, v6, v12, s41
	global_store_short_d16_hi v4, v6, s[2:3]
	v_mul_f32_e32 v4, v46, v5
	v_bfe_u32 v6, v4, 16, 1
	v_add3_u32 v4, v4, v6, s41
	v_add_u32_e32 v6, 0x12040, v3
	global_store_short_d16_hi v6, v4, s[2:3]
	v_mul_f32_e32 v4, v30, v5
	v_bfe_u32 v6, v4, 16, 1
	v_add3_u32 v4, v4, v6, s41
	v_add_u32_e32 v6, 0x12080, v3
	global_store_short_d16_hi v6, v4, s[2:3]
	v_mul_f32_e32 v4, v14, v5
	v_bfe_u32 v5, v4, 16, 1
	v_add3_u32 v4, v4, v5, s41
	v_rcp_f32_e32 v5, v7
	v_add_u32_e32 v6, 0x120c0, v3
	global_store_short_d16_hi v6, v4, s[2:3]
	v_add_u32_e32 v4, 0x13000, v3
	v_mul_f32_e32 v6, v63, v5
	v_bfe_u32 v7, v6, 16, 1
	v_add3_u32 v6, v6, v7, s41
	global_store_short_d16_hi v4, v6, s[2:3]
	v_mul_f32_e32 v4, v47, v5
	v_bfe_u32 v6, v4, 16, 1
	v_add3_u32 v4, v4, v6, s41
	v_add_u32_e32 v6, 0x13040, v3
	global_store_short_d16_hi v6, v4, s[2:3]
	v_mul_f32_e32 v4, v31, v5
	v_bfe_u32 v6, v4, 16, 1
	v_add3_u32 v4, v4, v6, s41
	v_add_u32_e32 v6, 0x13080, v3
	global_store_short_d16_hi v6, v4, s[2:3]
	v_mul_f32_e32 v4, v15, v5
	v_bfe_u32 v5, v4, 16, 1
	v_add3_u32 v4, v4, v5, s41
	v_rcp_f32_e32 v5, v8
	v_add_u32_e32 v6, 0x130c0, v3
	global_store_short_d16_hi v6, v4, s[2:3]
	v_add_u32_e32 v4, 0x18000, v3
	v_mul_f32_e32 v6, v64, v5
	v_bfe_u32 v7, v6, 16, 1
	v_add3_u32 v6, v6, v7, s41
	global_store_short_d16_hi v4, v6, s[2:3]
	v_mul_f32_e32 v4, v48, v5
	v_bfe_u32 v6, v4, 16, 1
	v_add3_u32 v4, v4, v6, s41
	v_add_u32_e32 v6, 0x18040, v3
	global_store_short_d16_hi v6, v4, s[2:3]
	v_mul_f32_e32 v4, v32, v5
	v_bfe_u32 v6, v4, 16, 1
	v_add3_u32 v4, v4, v6, s41
	v_add_u32_e32 v6, 0x18080, v3
	global_store_short_d16_hi v6, v4, s[2:3]
	v_mul_f32_e32 v4, v16, v5
	v_bfe_u32 v5, v4, 16, 1
	v_add3_u32 v4, v4, v5, s41
	v_rcp_f32_e32 v5, v9
	v_add_u32_e32 v6, 0x180c0, v3
	global_store_short_d16_hi v6, v4, s[2:3]
	v_add_u32_e32 v4, 0x19000, v3
	v_mul_f32_e32 v6, v65, v5
	v_bfe_u32 v7, v6, 16, 1
	v_add3_u32 v6, v6, v7, s41
	global_store_short_d16_hi v4, v6, s[2:3]
	v_mul_f32_e32 v4, v49, v5
	v_bfe_u32 v6, v4, 16, 1
	v_add3_u32 v4, v4, v6, s41
	v_add_u32_e32 v6, 0x19040, v3
	global_store_short_d16_hi v6, v4, s[2:3]
	v_mul_f32_e32 v4, v33, v5
	v_bfe_u32 v6, v4, 16, 1
	v_add3_u32 v4, v4, v6, s41
	v_add_u32_e32 v6, 0x19080, v3
	global_store_short_d16_hi v6, v4, s[2:3]
	v_mul_f32_e32 v4, v17, v5
	v_bfe_u32 v5, v4, 16, 1
	v_add3_u32 v4, v4, v5, s41
	v_rcp_f32_e32 v5, v10
	v_add_u32_e32 v6, 0x190c0, v3
	global_store_short_d16_hi v6, v4, s[2:3]
	v_add_u32_e32 v4, 0x1a000, v3
	v_mul_f32_e32 v6, v66, v5
	v_bfe_u32 v7, v6, 16, 1
	v_add3_u32 v6, v6, v7, s41
	global_store_short_d16_hi v4, v6, s[2:3]
	v_mul_f32_e32 v4, v50, v5
	v_bfe_u32 v6, v4, 16, 1
	v_add3_u32 v4, v4, v6, s41
	v_add_u32_e32 v6, 0x1a040, v3
	global_store_short_d16_hi v6, v4, s[2:3]
	v_mul_f32_e32 v4, v34, v5
	v_bfe_u32 v6, v4, 16, 1
	v_add3_u32 v4, v4, v6, s41
	v_add_u32_e32 v6, 0x1a080, v3
	global_store_short_d16_hi v6, v4, s[2:3]
	v_mul_f32_e32 v4, v18, v5
	v_bfe_u32 v5, v4, 16, 1
	v_add3_u32 v4, v4, v5, s41
	v_rcp_f32_e32 v5, v11
	v_add_u32_e32 v6, 0x1a0c0, v3
	global_store_short_d16_hi v6, v4, s[2:3]
	v_add_u32_e32 v4, 0x1b000, v3
	v_mul_f32_e32 v6, v67, v5
	v_bfe_u32 v7, v6, 16, 1
	v_add3_u32 v6, v6, v7, s41
	global_store_short_d16_hi v4, v6, s[2:3]
	v_mul_f32_e32 v4, v51, v5
	v_bfe_u32 v6, v4, 16, 1
	v_add3_u32 v4, v4, v6, s41
	v_add_u32_e32 v6, 0x1b040, v3
	global_store_short_d16_hi v6, v4, s[2:3]
	v_mul_f32_e32 v4, v35, v5
	v_bfe_u32 v6, v4, 16, 1
	v_add3_u32 v4, v4, v6, s41
	v_add_u32_e32 v6, 0x1b080, v3
	global_store_short_d16_hi v6, v4, s[2:3]
	v_mul_f32_e32 v4, v19, v5
	v_bfe_u32 v5, v4, 16, 1
	v_add3_u32 v4, v4, v5, s41
	v_add_u32_e32 v3, 0x1b0c0, v3
	global_store_short_d16_hi v3, v4, s[2:3]
	s_waitcnt lgkmcnt(0)
	s_add_i32 s42, s42, s96
	s_add_i32 s24, s24, s25
	s_cmpk_gt_i32 s42, 0x1ff
	s_nop 0
	s_barrier
	s_cbranch_scc1 .LBB0_3441
